# v50 + nt on the WIN silu-tile stores (q and gate outputs, first read two phases later; the source's nontemporal q store was dropped by the compiler)
# baseline (speedup 1.0000x reference)
.LBB0_1029:
	s_lshl_b32 s14, s16, 8
	s_and_b32 s43, s14, 0x300
	s_lshl_b32 s14, s2, 8
	s_ashr_i32 s15, s14, 31
	s_lshl_b64 s[14:15], s[14:15], 11
	s_add_u32 s2, s64, s14
	s_addc_u32 s14, s65, s15
	s_lshl_b32 s15, s43, 1
	s_add_u32 s64, s2, s15
	s_addc_u32 s65, s14, 0
	s_add_i32 s2, s6, -1
	s_cmp_gt_u32 s2, 1
	s_mov_b64 s[14:15], -1
	s_cbranch_scc0 .LBB0_1036
	s_cmp_lg_u32 s6, 3
	s_cbranch_scc0 .LBB0_1032
	v_mul_f32_e32 v132, 0xbfb8aa3b, v126
	v_mul_f32_e32 v133, 0xbfb8aa3b, v127
	v_exp_f32_e32 v132, v132
	v_exp_f32_e32 v133, v133
	v_mov_b32_e32 v131, v170
	v_mov_b32_e32 v130, v1
	v_pk_add_f32 v[132:133], v[132:133], 1.0 op_sel_hi:[1,0]
	v_add_u32_e32 v130, s77, v130
	v_lshl_add_u32 v138, v131, 3, s78
	v_ashrrev_i32_e32 v131, 31, v130
	v_lshlrev_b64 v[140:141], 11, v[130:131]
	v_mul_f32_e32 v131, 0xbfb8aa3b, v122
	v_exp_f32_e32 v134, v131
	v_mul_f32_e32 v135, 0xbfb8aa3b, v123
	v_rcp_f32_e32 v131, v133
	v_exp_f32_e32 v135, v135
	v_mul_f32_e32 v131, v127, v131
	v_pk_add_f32 v[134:135], v[134:135], 1.0 op_sel_hi:[1,0]
	v_rcp_f32_e32 v133, v132
	v_lshl_add_u64 v[140:141], s[64:65], 0, v[140:141]
	v_mul_f32_e32 v136, v126, v133
	v_rcp_f32_e32 v132, v135
	s_nop 0
	v_mul_f32_e32 v139, v123, v132
	v_mul_f32_e32 v132, 0xbfb8aa3b, v128
	v_mul_f32_e32 v133, 0xbfb8aa3b, v129
	v_exp_f32_e32 v132, v132
	v_exp_f32_e32 v133, v133
	v_rcp_f32_e32 v135, v134
	v_pk_add_f32 v[132:133], v[132:133], 1.0 op_sel_hi:[1,0]
	v_mul_f32_e32 v143, v122, v135
	v_mul_f32_e32 v134, 0xbfb8aa3b, v124
	v_exp_f32_e32 v134, v134
	v_rcp_f32_e32 v135, v133
	s_nop 0
	v_mul_f32_e32 v133, v129, v135
	v_mul_f32_e32 v135, 0xbfb8aa3b, v125
	v_exp_f32_e32 v135, v135
	s_nop 0
	v_pk_add_f32 v[134:135], v[134:135], 1.0 op_sel_hi:[1,0]
	v_rcp_f32_e32 v137, v132
	s_nop 0
	v_mul_f32_e32 v132, v128, v137
	v_rcp_f32_e32 v137, v135
	v_rcp_f32_e32 v135, v134
	v_mul_f32_e32 v137, v125, v137
	v_mul_f32_e32 v142, v124, v135
	v_cvt_pk_bf16_f32 v134, v136, v131
	v_mul_f32_e32 v131, 0xbfb8aa3b, v118
	v_cvt_pk_bf16_f32 v137, v142, v137
	v_exp_f32_e32 v142, v131
	v_mul_f32_e32 v131, 0xbfb8aa3b, v119
	v_cvt_pk_bf16_f32 v136, v143, v139
	v_exp_f32_e32 v143, v131
	v_ashrrev_i32_e32 v139, 31, v138
	v_cvt_pk_bf16_f32 v135, v132, v133
	v_lshlrev_b64 v[132:133], 1, v[138:139]
	v_lshl_add_u64 v[138:139], v[140:141], 0, v[132:133]
	v_pk_add_f32 v[140:141], v[142:143], 1.0 op_sel_hi:[1,0]
	global_store_dwordx4 v[138:139], v[134:137], off nt
	s_nop 1
	v_mul_f32_e32 v134, 0xbfb8aa3b, v114
	v_exp_f32_e32 v134, v134
	v_rcp_f32_e32 v131, v141
	v_mul_f32_e32 v135, 0xbfb8aa3b, v115
	v_exp_f32_e32 v135, v135
	v_mul_f32_e32 v131, v119, v131
	v_pk_add_f32 v[134:135], v[134:135], 1.0 op_sel_hi:[1,0]
	v_rcp_f32_e32 v136, v140
	s_nop 0
	v_mul_f32_e32 v140, v118, v136
	v_rcp_f32_e32 v136, v135
	s_nop 0
	v_mul_f32_e32 v141, v115, v136
	v_mul_f32_e32 v136, 0xbfb8aa3b, v120
	v_mul_f32_e32 v137, 0xbfb8aa3b, v121
	v_exp_f32_e32 v136, v136
	v_exp_f32_e32 v137, v137
	v_rcp_f32_e32 v135, v134
	v_pk_add_f32 v[136:137], v[136:137], 1.0 op_sel_hi:[1,0]
	v_mul_f32_e32 v144, v114, v135
	v_mul_f32_e32 v134, 0xbfb8aa3b, v116
	v_exp_f32_e32 v134, v134
	v_rcp_f32_e32 v135, v137
	s_nop 0
	v_mul_f32_e32 v137, v121, v135
	v_mul_f32_e32 v135, 0xbfb8aa3b, v117
	v_exp_f32_e32 v135, v135
	s_nop 0
	v_pk_add_f32 v[134:135], v[134:135], 1.0 op_sel_hi:[1,0]
	v_rcp_f32_e32 v142, v136
	s_nop 0
	v_mul_f32_e32 v136, v120, v142
	v_rcp_f32_e32 v142, v135
	v_rcp_f32_e32 v135, v134
	v_mul_f32_e32 v142, v117, v142
	v_mul_f32_e32 v143, v116, v135
	v_cvt_pk_bf16_f32 v134, v140, v131
	v_mul_f32_e32 v131, 0xbfb8aa3b, v110
	v_exp_f32_e32 v140, v131
	v_mul_f32_e32 v131, 0xbfb8aa3b, v111
	v_cvt_pk_bf16_f32 v135, v136, v137
	v_cvt_pk_bf16_f32 v136, v144, v141
	v_exp_f32_e32 v141, v131
	v_cvt_pk_bf16_f32 v137, v143, v142
	global_store_dwordx4 v[138:139], v[134:137], off offset:256 nt
	s_nop 1
	s_nop 0
	v_pk_add_f32 v[136:137], v[140:141], 1.0 op_sel_hi:[1,0]
	v_add_u32_e32 v134, 16, v130
	v_ashrrev_i32_e32 v135, 31, v134
	v_lshlrev_b64 v[138:139], 11, v[134:135]
	v_mul_f32_e32 v134, 0xbfb8aa3b, v106
	v_exp_f32_e32 v134, v134
	v_rcp_f32_e32 v131, v137
	v_mul_f32_e32 v135, 0xbfb8aa3b, v107
	v_exp_f32_e32 v135, v135
	v_mul_f32_e32 v131, v111, v131
	v_pk_add_f32 v[134:135], v[134:135], 1.0 op_sel_hi:[1,0]
	v_rcp_f32_e32 v137, v136
	v_lshl_add_u64 v[138:139], s[64:65], 0, v[138:139]
	v_mul_f32_e32 v140, v110, v137
	v_rcp_f32_e32 v136, v135
	v_mul_f32_e32 v137, 0xbfb8aa3b, v113
	v_mul_f32_e32 v142, v107, v136
	v_mul_f32_e32 v136, 0xbfb8aa3b, v112
	v_exp_f32_e32 v136, v136
	v_exp_f32_e32 v137, v137
	v_rcp_f32_e32 v135, v134
	v_pk_add_f32 v[136:137], v[136:137], 1.0 op_sel_hi:[1,0]
	v_mul_f32_e32 v144, v106, v135
	v_mul_f32_e32 v134, 0xbfb8aa3b, v108
	v_exp_f32_e32 v134, v134
	v_lshl_add_u64 v[138:139], v[138:139], 0, v[132:133]
	v_rcp_f32_e32 v135, v137
	s_nop 0
	v_mul_f32_e32 v137, v113, v135
	v_mul_f32_e32 v135, 0xbfb8aa3b, v109
	v_exp_f32_e32 v135, v135
	s_nop 0
	v_pk_add_f32 v[134:135], v[134:135], 1.0 op_sel_hi:[1,0]
	v_rcp_f32_e32 v141, v136
	s_nop 0
	v_mul_f32_e32 v136, v112, v141
	v_rcp_f32_e32 v141, v135
	v_rcp_f32_e32 v135, v134
	v_mul_f32_e32 v145, v109, v141
	v_mul_f32_e32 v143, v108, v135
	v_cvt_pk_bf16_f32 v134, v140, v131
	v_mul_f32_e32 v131, 0xbfb8aa3b, v102
	v_exp_f32_e32 v140, v131
	v_mul_f32_e32 v131, 0xbfb8aa3b, v103
	v_exp_f32_e32 v141, v131
	v_cvt_pk_bf16_f32 v135, v136, v137
	v_cvt_pk_bf16_f32 v136, v144, v142
	v_cvt_pk_bf16_f32 v137, v143, v145
	v_pk_add_f32 v[140:141], v[140:141], 1.0 op_sel_hi:[1,0]
	global_store_dwordx4 v[138:139], v[134:137], off nt
	s_nop 1
	v_mul_f32_e32 v134, 0xbfb8aa3b, v98
	v_exp_f32_e32 v134, v134
	v_rcp_f32_e32 v131, v141
	v_mul_f32_e32 v135, 0xbfb8aa3b, v99
	v_exp_f32_e32 v135, v135
	v_mul_f32_e32 v131, v103, v131
	v_pk_add_f32 v[134:135], v[134:135], 1.0 op_sel_hi:[1,0]
	v_rcp_f32_e32 v136, v140
	s_nop 0
	v_mul_f32_e32 v140, v102, v136
	v_rcp_f32_e32 v136, v135
	s_nop 0
	v_mul_f32_e32 v141, v99, v136
	v_mul_f32_e32 v136, 0xbfb8aa3b, v104
	v_mul_f32_e32 v137, 0xbfb8aa3b, v105
	v_exp_f32_e32 v136, v136
	v_exp_f32_e32 v137, v137
	v_rcp_f32_e32 v135, v134
	v_pk_add_f32 v[136:137], v[136:137], 1.0 op_sel_hi:[1,0]
	v_mul_f32_e32 v144, v98, v135
	v_mul_f32_e32 v134, 0xbfb8aa3b, v100
	v_exp_f32_e32 v134, v134
	v_rcp_f32_e32 v135, v137
	s_nop 0
	v_mul_f32_e32 v137, v105, v135
	v_mul_f32_e32 v135, 0xbfb8aa3b, v101
	v_exp_f32_e32 v135, v135
	s_nop 0
	v_pk_add_f32 v[134:135], v[134:135], 1.0 op_sel_hi:[1,0]
	v_rcp_f32_e32 v142, v136
	s_nop 0
	v_mul_f32_e32 v136, v104, v142
	v_rcp_f32_e32 v142, v135
	v_rcp_f32_e32 v135, v134
	v_mul_f32_e32 v142, v101, v142
	v_mul_f32_e32 v143, v100, v135
	v_cvt_pk_bf16_f32 v134, v140, v131
	v_mul_f32_e32 v131, 0xbfb8aa3b, v94
	v_exp_f32_e32 v140, v131
	v_mul_f32_e32 v131, 0xbfb8aa3b, v95
	v_cvt_pk_bf16_f32 v135, v136, v137
	v_cvt_pk_bf16_f32 v136, v144, v141
	v_exp_f32_e32 v141, v131
	v_cvt_pk_bf16_f32 v137, v143, v142
	global_store_dwordx4 v[138:139], v[134:137], off offset:256 nt
	s_nop 1
	s_nop 0
	v_pk_add_f32 v[136:137], v[140:141], 1.0 op_sel_hi:[1,0]
	v_add_u32_e32 v134, 32, v130
	v_ashrrev_i32_e32 v135, 31, v134
	v_lshlrev_b64 v[138:139], 11, v[134:135]
	v_mul_f32_e32 v134, 0xbfb8aa3b, v90
	v_exp_f32_e32 v134, v134
	v_rcp_f32_e32 v131, v137
	v_mul_f32_e32 v135, 0xbfb8aa3b, v91
	v_exp_f32_e32 v135, v135
	v_mul_f32_e32 v131, v95, v131
	v_pk_add_f32 v[134:135], v[134:135], 1.0 op_sel_hi:[1,0]
	v_rcp_f32_e32 v137, v136
	v_lshl_add_u64 v[138:139], s[64:65], 0, v[138:139]
	v_mul_f32_e32 v140, v94, v137
	v_rcp_f32_e32 v136, v135
	v_mul_f32_e32 v137, 0xbfb8aa3b, v97
	v_mul_f32_e32 v142, v91, v136
	v_mul_f32_e32 v136, 0xbfb8aa3b, v96
	v_exp_f32_e32 v136, v136
	v_exp_f32_e32 v137, v137
	v_rcp_f32_e32 v135, v134
	v_pk_add_f32 v[136:137], v[136:137], 1.0 op_sel_hi:[1,0]
	v_mul_f32_e32 v144, v90, v135
	v_mul_f32_e32 v134, 0xbfb8aa3b, v92
	v_exp_f32_e32 v134, v134
	v_lshl_add_u64 v[138:139], v[138:139], 0, v[132:133]
	v_rcp_f32_e32 v135, v137
	s_nop 0
	v_mul_f32_e32 v137, v97, v135
	v_mul_f32_e32 v135, 0xbfb8aa3b, v93
	v_exp_f32_e32 v135, v135
	s_nop 0
	v_pk_add_f32 v[134:135], v[134:135], 1.0 op_sel_hi:[1,0]
	v_rcp_f32_e32 v141, v136
	s_nop 0
	v_mul_f32_e32 v136, v96, v141
	v_rcp_f32_e32 v141, v135
	v_rcp_f32_e32 v135, v134
	v_mul_f32_e32 v145, v93, v141
	v_mul_f32_e32 v143, v92, v135
	v_cvt_pk_bf16_f32 v134, v140, v131
	v_mul_f32_e32 v131, 0xbfb8aa3b, v86
	v_exp_f32_e32 v140, v131
	v_mul_f32_e32 v131, 0xbfb8aa3b, v87
	v_exp_f32_e32 v141, v131
	v_cvt_pk_bf16_f32 v135, v136, v137
	v_cvt_pk_bf16_f32 v136, v144, v142
	v_cvt_pk_bf16_f32 v137, v143, v145
	v_pk_add_f32 v[140:141], v[140:141], 1.0 op_sel_hi:[1,0]
	global_store_dwordx4 v[138:139], v[134:137], off nt
	s_nop 1
	v_mul_f32_e32 v134, 0xbfb8aa3b, v82
	v_exp_f32_e32 v134, v134
	v_rcp_f32_e32 v131, v141
	v_mul_f32_e32 v135, 0xbfb8aa3b, v83
	v_exp_f32_e32 v135, v135
	v_mul_f32_e32 v131, v87, v131
	v_pk_add_f32 v[134:135], v[134:135], 1.0 op_sel_hi:[1,0]
	v_rcp_f32_e32 v136, v140
	s_nop 0
	v_mul_f32_e32 v140, v86, v136
	v_rcp_f32_e32 v136, v135
	s_nop 0
	v_mul_f32_e32 v141, v83, v136
	v_mul_f32_e32 v136, 0xbfb8aa3b, v88
	v_mul_f32_e32 v137, 0xbfb8aa3b, v89
	v_exp_f32_e32 v136, v136
	v_exp_f32_e32 v137, v137
	v_rcp_f32_e32 v135, v134
	v_pk_add_f32 v[136:137], v[136:137], 1.0 op_sel_hi:[1,0]
	v_mul_f32_e32 v144, v82, v135
	v_mul_f32_e32 v134, 0xbfb8aa3b, v84
	v_exp_f32_e32 v134, v134
	v_rcp_f32_e32 v135, v137
	s_nop 0
	v_mul_f32_e32 v137, v89, v135
	v_mul_f32_e32 v135, 0xbfb8aa3b, v85
	v_exp_f32_e32 v135, v135
	s_nop 0
	v_pk_add_f32 v[134:135], v[134:135], 1.0 op_sel_hi:[1,0]
	v_rcp_f32_e32 v142, v136
	s_nop 0
	v_mul_f32_e32 v136, v88, v142
	v_rcp_f32_e32 v142, v135
	v_rcp_f32_e32 v135, v134
	v_mul_f32_e32 v142, v85, v142
	v_mul_f32_e32 v143, v84, v135
	v_cvt_pk_bf16_f32 v134, v140, v131
	v_mul_f32_e32 v131, 0xbfb8aa3b, v78
	v_exp_f32_e32 v140, v131
	v_mul_f32_e32 v131, 0xbfb8aa3b, v79
	v_cvt_pk_bf16_f32 v135, v136, v137
	v_cvt_pk_bf16_f32 v136, v144, v141
	v_exp_f32_e32 v141, v131
	v_cvt_pk_bf16_f32 v137, v143, v142
	global_store_dwordx4 v[138:139], v[134:137], off offset:256 nt
	s_nop 1
	s_nop 0
	v_pk_add_f32 v[136:137], v[140:141], 1.0 op_sel_hi:[1,0]
	v_add_u32_e32 v134, 48, v130
	v_ashrrev_i32_e32 v135, 31, v134
	v_lshlrev_b64 v[138:139], 11, v[134:135]
	v_mul_f32_e32 v134, 0xbfb8aa3b, v74
	v_exp_f32_e32 v134, v134
	v_rcp_f32_e32 v131, v137
	v_mul_f32_e32 v135, 0xbfb8aa3b, v75
	v_exp_f32_e32 v135, v135
	v_mul_f32_e32 v131, v79, v131
	v_pk_add_f32 v[134:135], v[134:135], 1.0 op_sel_hi:[1,0]
	v_rcp_f32_e32 v137, v136
	v_lshl_add_u64 v[138:139], s[64:65], 0, v[138:139]
	v_mul_f32_e32 v140, v78, v137
	v_rcp_f32_e32 v136, v135
	v_mul_f32_e32 v137, 0xbfb8aa3b, v81
	v_mul_f32_e32 v142, v75, v136
	v_mul_f32_e32 v136, 0xbfb8aa3b, v80
	v_exp_f32_e32 v136, v136
	v_exp_f32_e32 v137, v137
	v_rcp_f32_e32 v135, v134
	v_pk_add_f32 v[136:137], v[136:137], 1.0 op_sel_hi:[1,0]
	v_mul_f32_e32 v144, v74, v135
	v_mul_f32_e32 v134, 0xbfb8aa3b, v76
	v_exp_f32_e32 v134, v134
	v_lshl_add_u64 v[138:139], v[138:139], 0, v[132:133]
	v_rcp_f32_e32 v135, v137
	s_nop 0
	v_mul_f32_e32 v137, v81, v135
	v_mul_f32_e32 v135, 0xbfb8aa3b, v77
	v_exp_f32_e32 v135, v135
	s_nop 0
	v_pk_add_f32 v[134:135], v[134:135], 1.0 op_sel_hi:[1,0]
	v_rcp_f32_e32 v141, v136
	s_nop 0
	v_mul_f32_e32 v136, v80, v141
	v_rcp_f32_e32 v141, v135
	v_rcp_f32_e32 v135, v134
	v_mul_f32_e32 v145, v77, v141
	v_mul_f32_e32 v143, v76, v135
	v_cvt_pk_bf16_f32 v134, v140, v131
	v_mul_f32_e32 v131, 0xbfb8aa3b, v70
	v_exp_f32_e32 v140, v131
	v_mul_f32_e32 v131, 0xbfb8aa3b, v71
	v_exp_f32_e32 v141, v131
	v_cvt_pk_bf16_f32 v135, v136, v137
	v_cvt_pk_bf16_f32 v136, v144, v142
	v_cvt_pk_bf16_f32 v137, v143, v145
	v_pk_add_f32 v[140:141], v[140:141], 1.0 op_sel_hi:[1,0]
	global_store_dwordx4 v[138:139], v[134:137], off nt
	s_nop 1
	v_mul_f32_e32 v134, 0xbfb8aa3b, v66
	v_exp_f32_e32 v134, v134
	v_rcp_f32_e32 v131, v141
	v_mul_f32_e32 v135, 0xbfb8aa3b, v67
	v_exp_f32_e32 v135, v135
	v_mul_f32_e32 v131, v71, v131
	v_pk_add_f32 v[134:135], v[134:135], 1.0 op_sel_hi:[1,0]
	v_rcp_f32_e32 v136, v140
	s_nop 0
	v_mul_f32_e32 v140, v70, v136
	v_rcp_f32_e32 v136, v135
	s_nop 0
	v_mul_f32_e32 v141, v67, v136
	v_mul_f32_e32 v136, 0xbfb8aa3b, v72
	v_mul_f32_e32 v137, 0xbfb8aa3b, v73
	v_exp_f32_e32 v136, v136
	v_exp_f32_e32 v137, v137
	v_rcp_f32_e32 v135, v134
	v_pk_add_f32 v[136:137], v[136:137], 1.0 op_sel_hi:[1,0]
	v_mul_f32_e32 v144, v66, v135
	v_mul_f32_e32 v134, 0xbfb8aa3b, v68
	v_exp_f32_e32 v134, v134
	v_rcp_f32_e32 v135, v137
	s_nop 0
	v_mul_f32_e32 v137, v73, v135
	v_mul_f32_e32 v135, 0xbfb8aa3b, v69
	v_exp_f32_e32 v135, v135
	s_nop 0
	v_pk_add_f32 v[134:135], v[134:135], 1.0 op_sel_hi:[1,0]
	v_rcp_f32_e32 v142, v136
	s_nop 0
	v_mul_f32_e32 v136, v72, v142
	v_rcp_f32_e32 v142, v135
	v_rcp_f32_e32 v135, v134
	v_mul_f32_e32 v142, v69, v142
	v_mul_f32_e32 v143, v68, v135
	v_cvt_pk_bf16_f32 v134, v140, v131
	v_mul_f32_e32 v131, 0xbfb8aa3b, v62
	v_exp_f32_e32 v140, v131
	v_mul_f32_e32 v131, 0xbfb8aa3b, v63
	v_cvt_pk_bf16_f32 v135, v136, v137
	v_cvt_pk_bf16_f32 v136, v144, v141
	v_exp_f32_e32 v141, v131
	v_cvt_pk_bf16_f32 v137, v143, v142
	global_store_dwordx4 v[138:139], v[134:137], off offset:256 nt
	s_nop 1
	s_nop 0
	v_pk_add_f32 v[136:137], v[140:141], 1.0 op_sel_hi:[1,0]
	v_add_u32_e32 v134, 0x80, v130
	v_ashrrev_i32_e32 v135, 31, v134
	v_lshlrev_b64 v[138:139], 11, v[134:135]
	v_mul_f32_e32 v134, 0xbfb8aa3b, v58
	v_exp_f32_e32 v134, v134
	v_rcp_f32_e32 v131, v137
	v_mul_f32_e32 v135, 0xbfb8aa3b, v59
	v_exp_f32_e32 v135, v135
	v_mul_f32_e32 v131, v63, v131
	v_pk_add_f32 v[134:135], v[134:135], 1.0 op_sel_hi:[1,0]
	v_rcp_f32_e32 v137, v136
	v_lshl_add_u64 v[138:139], s[64:65], 0, v[138:139]
	v_mul_f32_e32 v140, v62, v137
	v_rcp_f32_e32 v136, v135
	v_mul_f32_e32 v137, 0xbfb8aa3b, v65
	v_mul_f32_e32 v142, v59, v136
	v_mul_f32_e32 v136, 0xbfb8aa3b, v64
	v_exp_f32_e32 v136, v136
	v_exp_f32_e32 v137, v137
	v_rcp_f32_e32 v135, v134
	v_pk_add_f32 v[136:137], v[136:137], 1.0 op_sel_hi:[1,0]
	v_mul_f32_e32 v144, v58, v135
	v_mul_f32_e32 v134, 0xbfb8aa3b, v60
	v_exp_f32_e32 v134, v134
	v_lshl_add_u64 v[138:139], v[138:139], 0, v[132:133]
	v_rcp_f32_e32 v135, v137
	s_nop 0
	v_mul_f32_e32 v137, v65, v135
	v_mul_f32_e32 v135, 0xbfb8aa3b, v61
	v_exp_f32_e32 v135, v135
	s_nop 0
	v_pk_add_f32 v[134:135], v[134:135], 1.0 op_sel_hi:[1,0]
	v_rcp_f32_e32 v141, v136
	s_nop 0
	v_mul_f32_e32 v136, v64, v141
	v_rcp_f32_e32 v141, v135
	v_rcp_f32_e32 v135, v134
	v_mul_f32_e32 v145, v61, v141
	v_mul_f32_e32 v143, v60, v135
	v_cvt_pk_bf16_f32 v134, v140, v131
	v_mul_f32_e32 v131, 0xbfb8aa3b, v54
	v_exp_f32_e32 v140, v131
	v_mul_f32_e32 v131, 0xbfb8aa3b, v55
	v_exp_f32_e32 v141, v131
	v_cvt_pk_bf16_f32 v135, v136, v137
	v_cvt_pk_bf16_f32 v136, v144, v142
	v_cvt_pk_bf16_f32 v137, v143, v145
	v_pk_add_f32 v[140:141], v[140:141], 1.0 op_sel_hi:[1,0]
	global_store_dwordx4 v[138:139], v[134:137], off nt
	s_nop 1
	v_mul_f32_e32 v134, 0xbfb8aa3b, v50
	v_exp_f32_e32 v134, v134
	v_rcp_f32_e32 v131, v141
	v_mul_f32_e32 v135, 0xbfb8aa3b, v51
	v_exp_f32_e32 v135, v135
	v_mul_f32_e32 v131, v55, v131
	v_pk_add_f32 v[134:135], v[134:135], 1.0 op_sel_hi:[1,0]
	v_rcp_f32_e32 v136, v140
	s_nop 0
	v_mul_f32_e32 v140, v54, v136
	v_rcp_f32_e32 v136, v135
	s_nop 0
	v_mul_f32_e32 v141, v51, v136
	v_mul_f32_e32 v136, 0xbfb8aa3b, v56
	v_mul_f32_e32 v137, 0xbfb8aa3b, v57
	v_exp_f32_e32 v136, v136
	v_exp_f32_e32 v137, v137
	v_rcp_f32_e32 v135, v134
	v_pk_add_f32 v[136:137], v[136:137], 1.0 op_sel_hi:[1,0]
	v_mul_f32_e32 v144, v50, v135
	v_mul_f32_e32 v134, 0xbfb8aa3b, v52
	v_exp_f32_e32 v134, v134
	v_rcp_f32_e32 v135, v137
	s_nop 0
	v_mul_f32_e32 v137, v57, v135
	v_mul_f32_e32 v135, 0xbfb8aa3b, v53
	v_exp_f32_e32 v135, v135
	s_nop 0
	v_pk_add_f32 v[134:135], v[134:135], 1.0 op_sel_hi:[1,0]
	v_rcp_f32_e32 v142, v136
	s_nop 0
	v_mul_f32_e32 v136, v56, v142
	v_rcp_f32_e32 v142, v135
	v_rcp_f32_e32 v135, v134
	v_mul_f32_e32 v142, v53, v142
	v_mul_f32_e32 v143, v52, v135
	v_cvt_pk_bf16_f32 v134, v140, v131
	v_mul_f32_e32 v131, 0xbfb8aa3b, v46
	v_exp_f32_e32 v140, v131
	v_mul_f32_e32 v131, 0xbfb8aa3b, v47
	v_cvt_pk_bf16_f32 v135, v136, v137
	v_cvt_pk_bf16_f32 v136, v144, v141
	v_exp_f32_e32 v141, v131
	v_cvt_pk_bf16_f32 v137, v143, v142
	global_store_dwordx4 v[138:139], v[134:137], off offset:256 nt
	s_nop 1
	s_nop 0
	v_pk_add_f32 v[136:137], v[140:141], 1.0 op_sel_hi:[1,0]
	v_add_u32_e32 v134, 0x90, v130
	v_ashrrev_i32_e32 v135, 31, v134
	v_lshlrev_b64 v[138:139], 11, v[134:135]
	v_mul_f32_e32 v134, 0xbfb8aa3b, v42
	v_exp_f32_e32 v134, v134
	v_rcp_f32_e32 v131, v137
	v_mul_f32_e32 v135, 0xbfb8aa3b, v43
	v_exp_f32_e32 v135, v135
	v_mul_f32_e32 v131, v47, v131
	v_pk_add_f32 v[134:135], v[134:135], 1.0 op_sel_hi:[1,0]
	v_rcp_f32_e32 v137, v136
	v_lshl_add_u64 v[138:139], s[64:65], 0, v[138:139]
	v_mul_f32_e32 v140, v46, v137
	v_rcp_f32_e32 v136, v135
	v_mul_f32_e32 v137, 0xbfb8aa3b, v49
	v_mul_f32_e32 v142, v43, v136
	v_mul_f32_e32 v136, 0xbfb8aa3b, v48
	v_exp_f32_e32 v136, v136
	v_exp_f32_e32 v137, v137
	v_rcp_f32_e32 v135, v134
	v_pk_add_f32 v[136:137], v[136:137], 1.0 op_sel_hi:[1,0]
	v_mul_f32_e32 v144, v42, v135
	v_mul_f32_e32 v134, 0xbfb8aa3b, v44
	v_exp_f32_e32 v134, v134
	v_lshl_add_u64 v[138:139], v[138:139], 0, v[132:133]
	v_rcp_f32_e32 v135, v137
	s_nop 0
	v_mul_f32_e32 v137, v49, v135
	v_mul_f32_e32 v135, 0xbfb8aa3b, v45
	v_exp_f32_e32 v135, v135
	s_nop 0
	v_pk_add_f32 v[134:135], v[134:135], 1.0 op_sel_hi:[1,0]
	v_rcp_f32_e32 v141, v136
	s_nop 0
	v_mul_f32_e32 v136, v48, v141
	v_rcp_f32_e32 v141, v135
	v_rcp_f32_e32 v135, v134
	v_mul_f32_e32 v145, v45, v141
	v_mul_f32_e32 v143, v44, v135
	v_cvt_pk_bf16_f32 v134, v140, v131
	v_mul_f32_e32 v131, 0xbfb8aa3b, v38
	v_exp_f32_e32 v140, v131
	v_mul_f32_e32 v131, 0xbfb8aa3b, v39
	v_exp_f32_e32 v141, v131
	v_cvt_pk_bf16_f32 v135, v136, v137
	v_cvt_pk_bf16_f32 v136, v144, v142
	v_cvt_pk_bf16_f32 v137, v143, v145
	v_pk_add_f32 v[140:141], v[140:141], 1.0 op_sel_hi:[1,0]
	global_store_dwordx4 v[138:139], v[134:137], off nt
	s_nop 1
	v_mul_f32_e32 v134, 0xbfb8aa3b, v34
	v_exp_f32_e32 v134, v134
	v_rcp_f32_e32 v131, v141
	v_mul_f32_e32 v135, 0xbfb8aa3b, v35
	v_exp_f32_e32 v135, v135
	v_mul_f32_e32 v131, v39, v131
	v_pk_add_f32 v[134:135], v[134:135], 1.0 op_sel_hi:[1,0]
	v_rcp_f32_e32 v136, v140
	s_nop 0
	v_mul_f32_e32 v140, v38, v136
	v_rcp_f32_e32 v136, v135
	s_nop 0
	v_mul_f32_e32 v141, v35, v136
	v_mul_f32_e32 v136, 0xbfb8aa3b, v40
	v_mul_f32_e32 v137, 0xbfb8aa3b, v41
	v_exp_f32_e32 v136, v136
	v_exp_f32_e32 v137, v137
	v_rcp_f32_e32 v135, v134
	v_pk_add_f32 v[136:137], v[136:137], 1.0 op_sel_hi:[1,0]
	v_mul_f32_e32 v144, v34, v135
	v_mul_f32_e32 v134, 0xbfb8aa3b, v36
	v_exp_f32_e32 v134, v134
	v_rcp_f32_e32 v135, v137
	s_nop 0
	v_mul_f32_e32 v137, v41, v135
	v_mul_f32_e32 v135, 0xbfb8aa3b, v37
	v_exp_f32_e32 v135, v135
	s_nop 0
	v_pk_add_f32 v[134:135], v[134:135], 1.0 op_sel_hi:[1,0]
	v_rcp_f32_e32 v142, v136
	s_nop 0
	v_mul_f32_e32 v136, v40, v142
	v_rcp_f32_e32 v142, v135
	v_rcp_f32_e32 v135, v134
	v_mul_f32_e32 v142, v37, v142
	v_mul_f32_e32 v143, v36, v135
	v_cvt_pk_bf16_f32 v134, v140, v131
	v_mul_f32_e32 v131, 0xbfb8aa3b, v30
	v_exp_f32_e32 v140, v131
	v_mul_f32_e32 v131, 0xbfb8aa3b, v31
	v_cvt_pk_bf16_f32 v135, v136, v137
	v_cvt_pk_bf16_f32 v136, v144, v141
	v_exp_f32_e32 v141, v131
	v_cvt_pk_bf16_f32 v137, v143, v142
	global_store_dwordx4 v[138:139], v[134:137], off offset:256 nt
	s_nop 1
	s_nop 0
	v_pk_add_f32 v[136:137], v[140:141], 1.0 op_sel_hi:[1,0]
	v_add_u32_e32 v134, 0xa0, v130
	v_ashrrev_i32_e32 v135, 31, v134
	v_lshlrev_b64 v[138:139], 11, v[134:135]
	v_mul_f32_e32 v134, 0xbfb8aa3b, v26
	v_exp_f32_e32 v134, v134
	v_rcp_f32_e32 v131, v137
	v_mul_f32_e32 v135, 0xbfb8aa3b, v27
	v_exp_f32_e32 v135, v135
	v_mul_f32_e32 v131, v31, v131
	v_pk_add_f32 v[134:135], v[134:135], 1.0 op_sel_hi:[1,0]
	v_rcp_f32_e32 v137, v136
	v_lshl_add_u64 v[138:139], s[64:65], 0, v[138:139]
	v_mul_f32_e32 v140, v30, v137
	v_rcp_f32_e32 v136, v135
	v_mul_f32_e32 v137, 0xbfb8aa3b, v33
	v_mul_f32_e32 v142, v27, v136
	v_mul_f32_e32 v136, 0xbfb8aa3b, v32
	v_exp_f32_e32 v136, v136
	v_exp_f32_e32 v137, v137
	v_rcp_f32_e32 v135, v134
	v_pk_add_f32 v[136:137], v[136:137], 1.0 op_sel_hi:[1,0]
	v_mul_f32_e32 v144, v26, v135
	v_mul_f32_e32 v134, 0xbfb8aa3b, v28
	v_exp_f32_e32 v134, v134
	v_lshl_add_u64 v[138:139], v[138:139], 0, v[132:133]
	v_add_u32_e32 v130, 0xb0, v130
	v_rcp_f32_e32 v135, v137
	s_nop 0
	v_mul_f32_e32 v137, v33, v135
	v_mul_f32_e32 v135, 0xbfb8aa3b, v29
	v_exp_f32_e32 v135, v135
	s_nop 0
	v_pk_add_f32 v[134:135], v[134:135], 1.0 op_sel_hi:[1,0]
	v_rcp_f32_e32 v141, v136
	s_nop 0
	v_mul_f32_e32 v136, v32, v141
	v_rcp_f32_e32 v141, v135
	v_rcp_f32_e32 v135, v134
	v_mul_f32_e32 v145, v29, v141
	v_mul_f32_e32 v143, v28, v135
	v_cvt_pk_bf16_f32 v134, v140, v131
	v_mul_f32_e32 v131, 0xbfb8aa3b, v22
	v_exp_f32_e32 v140, v131
	v_mul_f32_e32 v131, 0xbfb8aa3b, v23
	v_exp_f32_e32 v141, v131
	v_cvt_pk_bf16_f32 v135, v136, v137
	v_cvt_pk_bf16_f32 v136, v144, v142
	v_cvt_pk_bf16_f32 v137, v143, v145
	v_pk_add_f32 v[140:141], v[140:141], 1.0 op_sel_hi:[1,0]
	global_store_dwordx4 v[138:139], v[134:137], off nt
	s_nop 1
	v_mul_f32_e32 v134, 0xbfb8aa3b, v18
	v_exp_f32_e32 v134, v134
	v_rcp_f32_e32 v131, v141
	v_mul_f32_e32 v135, 0xbfb8aa3b, v19
	v_exp_f32_e32 v135, v135
	v_mul_f32_e32 v131, v23, v131
	v_pk_add_f32 v[134:135], v[134:135], 1.0 op_sel_hi:[1,0]
	v_rcp_f32_e32 v136, v140
	s_nop 0
	v_mul_f32_e32 v140, v22, v136
	v_rcp_f32_e32 v136, v135
	s_nop 0
	v_mul_f32_e32 v141, v19, v136
	v_mul_f32_e32 v136, 0xbfb8aa3b, v24
	v_mul_f32_e32 v137, 0xbfb8aa3b, v25
	v_exp_f32_e32 v136, v136
	v_exp_f32_e32 v137, v137
	v_rcp_f32_e32 v135, v134
	v_pk_add_f32 v[136:137], v[136:137], 1.0 op_sel_hi:[1,0]
	v_mul_f32_e32 v144, v18, v135
	v_mul_f32_e32 v134, 0xbfb8aa3b, v20
	v_exp_f32_e32 v134, v134
	v_rcp_f32_e32 v135, v137
	s_nop 0
	v_mul_f32_e32 v137, v25, v135
	v_mul_f32_e32 v135, 0xbfb8aa3b, v21
	v_exp_f32_e32 v135, v135
	s_nop 0
	v_pk_add_f32 v[134:135], v[134:135], 1.0 op_sel_hi:[1,0]
	v_rcp_f32_e32 v142, v136
	s_nop 0
	v_mul_f32_e32 v136, v24, v142
	v_rcp_f32_e32 v142, v135
	v_rcp_f32_e32 v135, v134
	v_mul_f32_e32 v142, v21, v142
	v_mul_f32_e32 v143, v20, v135
	v_cvt_pk_bf16_f32 v134, v140, v131
	v_mul_f32_e32 v131, 0xbfb8aa3b, v14
	v_exp_f32_e32 v140, v131
	v_mul_f32_e32 v131, 0xbfb8aa3b, v15
	v_cvt_pk_bf16_f32 v135, v136, v137
	v_cvt_pk_bf16_f32 v136, v144, v141
	v_exp_f32_e32 v141, v131
	v_cvt_pk_bf16_f32 v137, v143, v142
	global_store_dwordx4 v[138:139], v[134:137], off offset:256 nt
	v_ashrrev_i32_e32 v131, 31, v130
	v_lshlrev_b64 v[130:131], 11, v[130:131]
	v_pk_add_f32 v[134:135], v[140:141], 1.0 op_sel_hi:[1,0]
	v_mul_f32_e32 v136, 0xbfb8aa3b, v10
	v_exp_f32_e32 v136, v136
	v_lshl_add_u64 v[130:131], s[64:65], 0, v[130:131]
	v_rcp_f32_e32 v137, v135
	s_nop 0
	v_mul_f32_e32 v138, v15, v137
	v_mul_f32_e32 v137, 0xbfb8aa3b, v11
	v_exp_f32_e32 v137, v137
	s_nop 0
	v_pk_add_f32 v[136:137], v[136:137], 1.0 op_sel_hi:[1,0]
	v_rcp_f32_e32 v135, v134
	v_rcp_f32_e32 v134, v137
	v_mul_f32_e32 v140, v14, v135
	v_mul_f32_e32 v142, v11, v134
	v_mul_f32_e32 v134, 0xbfb8aa3b, v16
	v_mul_f32_e32 v135, 0xbfb8aa3b, v17
	v_exp_f32_e32 v134, v134
	v_exp_f32_e32 v135, v135
	v_rcp_f32_e32 v137, v136
	v_pk_add_f32 v[134:135], v[134:135], 1.0 op_sel_hi:[1,0]
	v_mul_f32_e32 v143, v10, v137
	v_mul_f32_e32 v136, 0xbfb8aa3b, v12
	v_exp_f32_e32 v136, v136
	v_rcp_f32_e32 v137, v135
	s_nop 0
	v_mul_f32_e32 v135, v17, v137
	v_mul_f32_e32 v137, 0xbfb8aa3b, v13
	v_exp_f32_e32 v137, v137
	s_nop 0
	v_pk_add_f32 v[136:137], v[136:137], 1.0 op_sel_hi:[1,0]
	v_rcp_f32_e32 v139, v134
	s_nop 0
	v_mul_f32_e32 v139, v16, v139
	v_cvt_pk_bf16_f32 v135, v139, v135
	v_rcp_f32_e32 v134, v137
	v_mul_f32_e32 v139, 0xbfb8aa3b, v7
	v_mul_f32_e32 v137, v13, v134
	v_rcp_f32_e32 v134, v136
	s_nop 0
	v_mul_f32_e32 v141, v12, v134
	v_cvt_pk_bf16_f32 v134, v140, v138
	v_mul_f32_e32 v138, 0xbfb8aa3b, v6
	v_exp_f32_e32 v138, v138
	v_exp_f32_e32 v139, v139
	v_cvt_pk_bf16_f32 v137, v141, v137
	v_lshl_add_u64 v[140:141], v[130:131], 0, v[132:133]
	v_cvt_pk_bf16_f32 v136, v143, v142
	v_pk_add_f32 v[130:131], v[138:139], 1.0 op_sel_hi:[1,0]
	global_store_dwordx4 v[140:141], v[134:137], off nt
	v_mul_f32_e32 v132, 0xbfb8aa3b, v2
	v_exp_f32_e32 v132, v132
	v_rcp_f32_e32 v133, v131
	s_nop 0
	v_mul_f32_e32 v135, v7, v133
	v_mul_f32_e32 v133, 0xbfb8aa3b, v3
	v_exp_f32_e32 v133, v133
	s_nop 0
	v_pk_add_f32 v[132:133], v[132:133], 1.0 op_sel_hi:[1,0]
	v_rcp_f32_e32 v131, v130
	v_rcp_f32_e32 v130, v133
	v_mul_f32_e32 v136, v6, v131
	v_mul_f32_e32 v138, v3, v130
	v_mul_f32_e32 v130, 0xbfb8aa3b, v8
	v_mul_f32_e32 v131, 0xbfb8aa3b, v9
	v_exp_f32_e32 v130, v130
	v_exp_f32_e32 v131, v131
	v_rcp_f32_e32 v133, v132
	v_pk_add_f32 v[130:131], v[130:131], 1.0 op_sel_hi:[1,0]
	v_mul_f32_e32 v139, v2, v133
	v_mul_f32_e32 v132, 0xbfb8aa3b, v4
	v_exp_f32_e32 v132, v132
	v_rcp_f32_e32 v133, v131
	s_nop 0
	v_mul_f32_e32 v131, v9, v133
	v_mul_f32_e32 v133, 0xbfb8aa3b, v5
	v_exp_f32_e32 v133, v133
	s_nop 0
	v_pk_add_f32 v[132:133], v[132:133], 1.0 op_sel_hi:[1,0]
	v_rcp_f32_e32 v134, v130
	s_nop 0
	v_mul_f32_e32 v134, v8, v134
	v_cvt_pk_bf16_f32 v131, v134, v131
	v_rcp_f32_e32 v130, v133
	s_nop 0
	v_mul_f32_e32 v133, v5, v130
	s_mov_b64 s[14:15], 0
	v_rcp_f32_e32 v130, v132
	s_nop 0
	v_mul_f32_e32 v137, v4, v130
	v_cvt_pk_bf16_f32 v130, v136, v135
	v_cvt_pk_bf16_f32 v132, v139, v138
	v_cvt_pk_bf16_f32 v133, v137, v133
	global_store_dwordx4 v[140:141], v[130:133], off offset:256 nt
